# grid barrier: non-leader workgroups poll the top-level generation word directly (one hop less)
# speedup vs baseline: 1.0107x; 1.0092x over previous
; __device__ __forceinline__ unsigned xb_ld(unsigned* p)              { return __hip_atomic_load(p, __ATOMIC_RELAXED, __HIP_MEMORY_SCOPE_AGENT); }
; __device__ __forceinline__ unsigned xb_add(unsigned* p, unsigned v) { return __hip_atomic_fetch_add(p, v, __ATOMIC_RELAXED, __HIP_MEMORY_SCOPE_AGENT); }
; #define XB_SPIN(cond, bar) do { unsigned _sp = 0; while (cond) { __builtin_amdgcn_s_sleep(1); \
;     if ((++_sp & 255u) == 0u) { if (xb_ld(&(bar)[XB_TMO])) break; if (_sp > XB_SPIN_CAP) { atomicAdd(&(bar)[XB_TMO], 1u); break; } } } } while (0)
; __device__ __forceinline__ void xcd_barrier(unsigned* bar, volatile LAS unsigned* st) {
;     ...
;     const unsigned old = xb_add(&bar[XB_XSUB(x)], 1u);
;     const unsigned gen = old / nloc;
;     if (old + 1u == (gen + 1u) * nloc) {
;       __builtin_amdgcn_fence(__ATOMIC_RELEASE, "agent");
;       asm volatile("s_waitcnt vmcnt(0)" ::: "memory");
;       const unsigned og = xb_add(&bar[XB_TOP], 1u);
;       const unsigned tg = og / nx;
;       if (og + 1u == (tg + 1u) * nx) xb_add(&bar[XB_TOPGEN], 1u);
;       else XB_SPIN(xb_ld(&bar[XB_TOPGEN]) == tg, bar);
;       __builtin_amdgcn_fence(__ATOMIC_ACQUIRE, "agent");
;       xb_add(&bar[XB_XGEN(x)], 1u);
;       asm volatile("s_waitcnt vmcnt(0)" ::: "memory");
;     } else {
;       XB_SPIN(xb_ld(&bar[XB_XGEN(x)]) == gen, bar);
.LBB0_177:
	s_or_b64 exec, exec, s[2:3]
	v_cvt_f32_u32_e32 v4, v2
	s_waitcnt vmcnt(0)
	v_readfirstlane_b32 s0, v3
	v_sub_u32_e32 v3, 0, v2
	v_rcp_iflag_f32_e32 v4, v4
	v_add_u32_e32 v5, s0, v1
	v_mul_f32_e32 v4, 0x4f7ffffe, v4
	v_cvt_u32_f32_e32 v4, v4
	v_mul_lo_u32 v1, v3, v4
	v_mul_hi_u32 v1, v4, v1
	v_add_u32_e32 v1, v4, v1
	v_mul_hi_u32 v1, v5, v1
	v_mul_lo_u32 v3, v1, v2
	v_sub_u32_e32 v3, v5, v3
	v_add_u32_e32 v4, 1, v1
	v_cmp_ge_u32_e32 vcc, v3, v2
	s_nop 1
	v_cndmask_b32_e32 v1, v1, v4, vcc
	v_sub_u32_e32 v4, v3, v2
	v_cndmask_b32_e32 v3, v3, v4, vcc
	v_add_u32_e32 v4, 1, v1
	v_cmp_ge_u32_e32 vcc, v3, v2
	v_add_u32_e32 v3, 1, v5
	s_nop 0
	v_cndmask_b32_e32 v1, v1, v4, vcc
	v_mul_lo_u32 v4, v2, v1
	v_add_u32_e32 v2, v4, v2
	v_cmp_ne_u32_e32 vcc, v3, v2
	s_and_saveexec_b64 s[0:1], vcc
	s_xor_b64 s[0:1], exec, s[0:1]
	s_cbranch_execz .LBB0_191
	v_mov_b32_e32 v0, 0x3000
	global_load_dword v0, v0, s[8:9] offset:1280 sc1
	s_add_u32 s4, s8, 0x3500
	s_addc_u32 s5, s9, 0
	s_waitcnt vmcnt(0)
	v_cmp_eq_u32_e32 vcc, v0, v1
	s_and_saveexec_b64 s[2:3], vcc
	s_cbranch_execz .LBB0_190
	s_mov_b32 s22, 1
	s_mov_b64 s[12:13], 0
	v_mov_b32_e32 v0, 0
	s_branch .LBB0_181

; __device__ __forceinline__ unsigned xb_ld(unsigned* p)              { return __hip_atomic_load(p, __ATOMIC_RELAXED, __HIP_MEMORY_SCOPE_AGENT); }
; __device__ __forceinline__ unsigned xb_add(unsigned* p, unsigned v) { return __hip_atomic_fetch_add(p, v, __ATOMIC_RELAXED, __HIP_MEMORY_SCOPE_AGENT); }
; #define XB_SPIN(cond, bar) do { unsigned _sp = 0; while (cond) { __builtin_amdgcn_s_sleep(1); \
;     if ((++_sp & 255u) == 0u) { if (xb_ld(&(bar)[XB_TMO])) break; if (_sp > XB_SPIN_CAP) { atomicAdd(&(bar)[XB_TMO], 1u); break; } } } } while (0)
; __device__ __forceinline__ void xcd_barrier(unsigned* bar, volatile LAS unsigned* st) {
;     ...
;     const unsigned old = xb_add(&bar[XB_XSUB(x)], 1u);
;     const unsigned gen = old / nloc;
;     if (old + 1u == (gen + 1u) * nloc) {
;       __builtin_amdgcn_fence(__ATOMIC_RELEASE, "agent");
;       asm volatile("s_waitcnt vmcnt(0)" ::: "memory");
;       const unsigned og = xb_add(&bar[XB_TOP], 1u);
;       const unsigned tg = og / nx;
;       if (og + 1u == (tg + 1u) * nx) xb_add(&bar[XB_TOPGEN], 1u);
;       else XB_SPIN(xb_ld(&bar[XB_TOPGEN]) == tg, bar);
;       __builtin_amdgcn_fence(__ATOMIC_ACQUIRE, "agent");
;       xb_add(&bar[XB_XGEN(x)], 1u);
;       asm volatile("s_waitcnt vmcnt(0)" ::: "memory");
;     } else {
;       XB_SPIN(xb_ld(&bar[XB_XGEN(x)]) == gen, bar);
.LBB0_245:
	s_or_b64 exec, exec, s[2:3]
	v_cvt_f32_u32_e32 v4, v2
	s_waitcnt vmcnt(0)
	v_readfirstlane_b32 s0, v3
	v_sub_u32_e32 v3, 0, v2
	v_rcp_iflag_f32_e32 v4, v4
	v_add_u32_e32 v5, s0, v1
	v_mul_f32_e32 v4, 0x4f7ffffe, v4
	v_cvt_u32_f32_e32 v4, v4
	v_mul_lo_u32 v1, v3, v4
	v_mul_hi_u32 v1, v4, v1
	v_add_u32_e32 v1, v4, v1
	v_mul_hi_u32 v1, v5, v1
	v_mul_lo_u32 v3, v1, v2
	v_sub_u32_e32 v3, v5, v3
	v_add_u32_e32 v4, 1, v1
	v_cmp_ge_u32_e32 vcc, v3, v2
	s_nop 1
	v_cndmask_b32_e32 v1, v1, v4, vcc
	v_sub_u32_e32 v4, v3, v2
	v_cndmask_b32_e32 v3, v3, v4, vcc
	v_add_u32_e32 v4, 1, v1
	v_cmp_ge_u32_e32 vcc, v3, v2
	v_add_u32_e32 v3, 1, v5
	s_nop 0
	v_cndmask_b32_e32 v1, v1, v4, vcc
	v_mul_lo_u32 v4, v2, v1
	v_add_u32_e32 v2, v4, v2
	v_cmp_ne_u32_e32 vcc, v3, v2
	s_and_saveexec_b64 s[0:1], vcc
	s_xor_b64 s[0:1], exec, s[0:1]
	s_cbranch_execz .LBB0_259
	v_mov_b32_e32 v0, 0x3000
	global_load_dword v0, v0, s[10:11] offset:1280 sc1
	s_add_u32 s4, s10, 0x3500
	s_addc_u32 s5, s11, 0
	s_waitcnt vmcnt(0)
	v_cmp_eq_u32_e32 vcc, v0, v1
	s_and_saveexec_b64 s[2:3], vcc
	s_cbranch_execz .LBB0_258
	s_mov_b32 s22, 1
	s_mov_b64 s[12:13], 0
	v_mov_b32_e32 v0, 0
	s_branch .LBB0_249

; __device__ __forceinline__ unsigned xb_ld(unsigned* p)              { return __hip_atomic_load(p, __ATOMIC_RELAXED, __HIP_MEMORY_SCOPE_AGENT); }
; __device__ __forceinline__ unsigned xb_add(unsigned* p, unsigned v) { return __hip_atomic_fetch_add(p, v, __ATOMIC_RELAXED, __HIP_MEMORY_SCOPE_AGENT); }
; #define XB_SPIN(cond, bar) do { unsigned _sp = 0; while (cond) { __builtin_amdgcn_s_sleep(1); \
;     if ((++_sp & 255u) == 0u) { if (xb_ld(&(bar)[XB_TMO])) break; if (_sp > XB_SPIN_CAP) { atomicAdd(&(bar)[XB_TMO], 1u); break; } } } } while (0)
; __device__ __forceinline__ void xcd_barrier(unsigned* bar, volatile LAS unsigned* st) {
;     ...
;     const unsigned old = xb_add(&bar[XB_XSUB(x)], 1u);
;     const unsigned gen = old / nloc;
;     if (old + 1u == (gen + 1u) * nloc) {
;       __builtin_amdgcn_fence(__ATOMIC_RELEASE, "agent");
;       asm volatile("s_waitcnt vmcnt(0)" ::: "memory");
;       const unsigned og = xb_add(&bar[XB_TOP], 1u);
;       const unsigned tg = og / nx;
;       if (og + 1u == (tg + 1u) * nx) xb_add(&bar[XB_TOPGEN], 1u);
;       else XB_SPIN(xb_ld(&bar[XB_TOPGEN]) == tg, bar);
;       __builtin_amdgcn_fence(__ATOMIC_ACQUIRE, "agent");
;       xb_add(&bar[XB_XGEN(x)], 1u);
;       asm volatile("s_waitcnt vmcnt(0)" ::: "memory");
;     } else {
;       XB_SPIN(xb_ld(&bar[XB_XGEN(x)]) == gen, bar);
.LBB0_1287:
	s_or_b64 exec, exec, s[2:3]
	v_cvt_f32_u32_e32 v4, v2
	s_waitcnt vmcnt(0)
	v_readfirstlane_b32 s0, v3
	v_sub_u32_e32 v3, 0, v2
	v_rcp_iflag_f32_e32 v4, v4
	v_add_u32_e32 v5, s0, v1
	v_mul_f32_e32 v4, 0x4f7ffffe, v4
	v_cvt_u32_f32_e32 v4, v4
	v_mul_lo_u32 v1, v3, v4
	v_mul_hi_u32 v1, v4, v1
	v_add_u32_e32 v1, v4, v1
	v_mul_hi_u32 v1, v5, v1
	v_mul_lo_u32 v3, v1, v2
	v_sub_u32_e32 v3, v5, v3
	v_add_u32_e32 v4, 1, v1
	v_cmp_ge_u32_e32 vcc, v3, v2
	s_nop 1
	v_cndmask_b32_e32 v1, v1, v4, vcc
	v_sub_u32_e32 v4, v3, v2
	v_cndmask_b32_e32 v3, v3, v4, vcc
	v_add_u32_e32 v4, 1, v1
	v_cmp_ge_u32_e32 vcc, v3, v2
	v_add_u32_e32 v3, 1, v5
	s_nop 0
	v_cndmask_b32_e32 v1, v1, v4, vcc
	v_mul_lo_u32 v4, v2, v1
	v_add_u32_e32 v2, v4, v2
	v_cmp_ne_u32_e32 vcc, v3, v2
	s_and_saveexec_b64 s[0:1], vcc
	s_xor_b64 s[0:1], exec, s[0:1]
	s_cbranch_execz .LBB0_1301
	v_mov_b32_e32 v0, 0x3000
	global_load_dword v0, v0, s[8:9] offset:1280 sc1
	s_add_u32 s4, s8, 0x3500
	s_addc_u32 s5, s9, 0
	s_waitcnt vmcnt(0)
	v_cmp_eq_u32_e32 vcc, v0, v1
	s_and_saveexec_b64 s[2:3], vcc
	s_cbranch_execz .LBB0_1300
	s_mov_b32 s23, 1
	s_mov_b64 s[12:13], 0
	v_mov_b32_e32 v0, 0
	s_branch .LBB0_1291

; __device__ __forceinline__ unsigned xb_ld(unsigned* p)              { return __hip_atomic_load(p, __ATOMIC_RELAXED, __HIP_MEMORY_SCOPE_AGENT); }
; __device__ __forceinline__ unsigned xb_add(unsigned* p, unsigned v) { return __hip_atomic_fetch_add(p, v, __ATOMIC_RELAXED, __HIP_MEMORY_SCOPE_AGENT); }
; #define XB_SPIN(cond, bar) do { unsigned _sp = 0; while (cond) { __builtin_amdgcn_s_sleep(1); \
;     if ((++_sp & 255u) == 0u) { if (xb_ld(&(bar)[XB_TMO])) break; if (_sp > XB_SPIN_CAP) { atomicAdd(&(bar)[XB_TMO], 1u); break; } } } } while (0)
; __device__ __forceinline__ void xcd_barrier(unsigned* bar, volatile LAS unsigned* st) {
;     ...
;     const unsigned old = xb_add(&bar[XB_XSUB(x)], 1u);
;     const unsigned gen = old / nloc;
;     if (old + 1u == (gen + 1u) * nloc) {
;       __builtin_amdgcn_fence(__ATOMIC_RELEASE, "agent");
;       asm volatile("s_waitcnt vmcnt(0)" ::: "memory");
;       const unsigned og = xb_add(&bar[XB_TOP], 1u);
;       const unsigned tg = og / nx;
;       if (og + 1u == (tg + 1u) * nx) xb_add(&bar[XB_TOPGEN], 1u);
;       else XB_SPIN(xb_ld(&bar[XB_TOPGEN]) == tg, bar);
;       __builtin_amdgcn_fence(__ATOMIC_ACQUIRE, "agent");
;       xb_add(&bar[XB_XGEN(x)], 1u);
;       asm volatile("s_waitcnt vmcnt(0)" ::: "memory");
;     } else {
;       XB_SPIN(xb_ld(&bar[XB_XGEN(x)]) == gen, bar);
.LBB0_2718:
	s_or_b64 exec, exec, s[2:3]
	v_cvt_f32_u32_e32 v4, v2
	s_waitcnt vmcnt(0)
	v_readfirstlane_b32 s0, v3
	v_sub_u32_e32 v3, 0, v2
	v_rcp_iflag_f32_e32 v4, v4
	v_add_u32_e32 v5, s0, v1
	v_mul_f32_e32 v4, 0x4f7ffffe, v4
	v_cvt_u32_f32_e32 v4, v4
	v_mul_lo_u32 v1, v3, v4
	v_mul_hi_u32 v1, v4, v1
	v_add_u32_e32 v1, v4, v1
	v_mul_hi_u32 v1, v5, v1
	v_mul_lo_u32 v3, v1, v2
	v_sub_u32_e32 v3, v5, v3
	v_add_u32_e32 v4, 1, v1
	v_cmp_ge_u32_e32 vcc, v3, v2
	s_nop 1
	v_cndmask_b32_e32 v1, v1, v4, vcc
	v_sub_u32_e32 v4, v3, v2
	v_cndmask_b32_e32 v3, v3, v4, vcc
	v_add_u32_e32 v4, 1, v1
	v_cmp_ge_u32_e32 vcc, v3, v2
	v_add_u32_e32 v3, 1, v5
	s_nop 0
	v_cndmask_b32_e32 v1, v1, v4, vcc
	v_mul_lo_u32 v4, v2, v1
	v_add_u32_e32 v2, v4, v2
	v_cmp_ne_u32_e32 vcc, v3, v2
	s_and_saveexec_b64 s[0:1], vcc
	s_xor_b64 s[0:1], exec, s[0:1]
	s_cbranch_execz .LBB0_2732
	v_mov_b32_e32 v0, 0x3000
	global_load_dword v0, v0, s[4:5] offset:1280 sc1
	s_add_u32 s10, s4, 0x3500
	s_addc_u32 s11, s5, 0
	s_waitcnt vmcnt(0)
	v_cmp_eq_u32_e32 vcc, v0, v1
	s_and_saveexec_b64 s[2:3], vcc
	s_cbranch_execz .LBB0_2731
	s_mov_b32 s22, 1
	s_mov_b64 s[12:13], 0
	v_mov_b32_e32 v0, 0
	s_branch .LBB0_2722
